# latent attention: static s_setprio 1 for waves 4-7 (reset at phase end), on top of the GEMM static raise
# speedup vs baseline: 1.0034x; 1.0034x over previous
.LBB0_577:
	v_readfirstlane_b32 s32, v135
	s_nop 1
	s_lshr_b32 s32, s32, 6
	s_cmp_ge_u32 s32, 4
	s_cbranch_scc0 .Lprio_at
	s_setprio 1

.LBB0_1880:
	s_setprio 0
	v_readlane_b32 s0, v251, 3
	v_readlane_b32 s1, v251, 4
	s_add_i32 s0, s0, 1
	v_writelane_b32 v251, s0, 3
	s_cmp_ge_i32 s0, s1
	s_nop 0
	v_writelane_b32 v251, s1, 4
	s_mov_b64 s[0:1], -1
	s_cbranch_scc0 .LBB0_1881
	s_getpc_b64 s[98:99]
